# v23 + HGRN2/GLA chunk loops no longer wait for the acknowledgement of their output-row stores (vmcnt in issue order: counted / relocated waits)
# baseline (speedup 1.0000x reference)
.LBB0_693:
	s_or_b64 exec, exec, s[18:19]
	s_add_i32 s18, s7, 63
	s_lshr_b32 s76, s18, 6
	s_add_u32 s16, s67, s16
	s_addc_u32 s17, s68, s17
	s_add_u32 s56, s16, s42
	s_addc_u32 s57, s17, 0
	s_and_b32 s16, s39, -4
	s_ashr_i32 s17, s16, 31
	s_lshl_b64 s[16:17], s[16:17], 2
	s_add_u32 s16, s69, s16
	s_addc_u32 s17, s70, s17
	s_lshl_b32 s18, s38, 2
	s_add_u32 s16, s16, s18
	v_lshlrev_b32_e32 v36, 3, v158
	s_addc_u32 s17, s17, 0
	v_and_b32_e32 v36, 24, v36
	s_ashr_i32 s20, s41, 7
	s_lshl_b32 s18, s40, 1
	v_mov_b32_e32 v1, v158
	v_lshl_or_b32 v141, s40, 5, v36
	s_and_b32 s21, s18, 2
	v_lshl_or_b32 v36, s20, 4, v161
	s_movk_i32 s18, 0x90
	v_mul_lo_u32 v37, v36, s18
	s_add_i32 s18, 0, 0x1dc00
	v_ashrrev_i32_e32 v35, 5, v1
	v_lshlrev_b32_e32 v1, 4, v1
	v_add_u32_e32 v142, s18, v37
	s_lshl_b32 s18, s40, 2
	v_and_b32_e32 v1, 0x1f0, v1
	v_mul_lo_u32 v35, v35, s84
	s_add_i32 s18, s18, 0
	v_add3_u32 v1, 0, v1, v35
	v_lshrrev_b32_e32 v35, 2, v161
	s_add_i32 s80, s18, 0x21000
	v_readlane_b32 s18, v252, 6
	v_lshlrev_b32_e32 v160, 2, v131
	v_or_b32_e32 v35, v130, v35
	v_mov_b32_e32 v131, s18
	s_movk_i32 s18, 0x110
	v_mad_u32_u24 v35, v35, s18, v131
	s_cmp_le_i32 s21, s20
	v_lshl_or_b32 v131, s21, 4, v160
	v_add_u32_e32 v157, 0, v138
	s_cselect_b64 s[18:19], -1, 0
	v_or_b32_e32 v138, 2, v131
	s_cmp_lt_i32 s21, s20
	s_mul_i32 s78, s21, 0x2100
	s_mul_i32 s79, s20, 0x2100
	v_cmp_gt_i32_e64 s[44:45], v138, v36
	v_or_b32_e32 v138, 3, v131
	s_cselect_b64 s[20:21], -1, 0
	v_or_b32_e32 v143, 17, v131
	s_lshl_b64 s[22:23], s[22:23], 1
	v_add_u32_e32 v37, 0, v136
	v_cmp_gt_u32_e64 s[38:39], 16, v140
	v_cmp_gt_i32_e64 s[40:41], v131, v36
	v_cmp_lt_i32_e64 s[42:43], v131, v36
	v_cmp_gt_i32_e64 s[46:47], v138, v36
	v_lshlrev_b32_e32 v138, 1, v131
	v_or_b32_e32 v140, 16, v131
	v_cmp_gt_i32_e64 s[50:51], v143, v36
	v_or_b32_e32 v143, 18, v131
	v_or_b32_e32 v131, 19, v131
	s_add_u32 s22, s56, s22
	s_waitcnt vmcnt(0) lgkmcnt(0)
	ds_write_b128 v1, v[70:73]
	ds_write_b128 v1, v[74:77] offset:33792
	ds_write_b128 v1, v[78:81] offset:8448
	ds_write_b128 v1, v[82:85] offset:42240
	ds_write_b128 v1, v[86:89] offset:16896
	ds_write_b128 v1, v[90:93] offset:50688
	ds_write_b128 v1, v[94:97] offset:25344
	ds_write_b128 v1, v[98:101] offset:59136
	v_lshlrev_b32_e32 v1, 4, v158
	v_add_u32_e32 v155, 0x20800, v37
	v_add_u32_e32 v163, 0x20c00, v37
	v_cmp_gt_i32_e64 s[48:49], v140, v36
	v_cmp_gt_i32_e64 s[52:53], v143, v36
	v_cmp_gt_i32_e64 s[54:55], v131, v36
	v_add_u32_e32 v180, 0x20840, v37
	v_add_u32_e32 v181, 0x20880, v37
	v_add_u32_e32 v182, 0x208c0, v37
	v_add_u32_e32 v183, 0x20900, v37
	v_add_u32_e32 v184, 0x20940, v37
	v_add_u32_e32 v185, 0x20980, v37
	v_add_u32_e32 v186, 0x209c0, v37
	v_add_u32_e32 v187, 0x20a00, v37
	v_add_u32_e32 v188, 0x20a40, v37
	v_add_u32_e32 v189, 0x20a80, v37
	v_add_u32_e32 v190, 0x20ac0, v37
	v_add_u32_e32 v191, 0x20b00, v37
	v_add_u32_e32 v192, 0x20b40, v37
	v_add_u32_e32 v193, 0x20b80, v37
	v_add_u32_e32 v194, 0x20bc0, v37
	v_add_u32_e32 v195, 0x20c40, v37
	v_add_u32_e32 v196, 0x20c80, v37
	v_add_u32_e32 v197, 0x20cc0, v37
	v_add_u32_e32 v198, 0x20d00, v37
	v_add_u32_e32 v199, 0x20d40, v37
	v_add_u32_e32 v200, 0x20d80, v37
	v_add_u32_e32 v201, 0x20dc0, v37
	v_add_u32_e32 v202, 0x20e00, v37
	v_add_u32_e32 v203, 0x20e40, v37
	v_add_u32_e32 v204, 0x20e80, v37
	v_add_u32_e32 v205, 0x20ec0, v37
	v_add_u32_e32 v206, 0x20f00, v37
	v_add_u32_e32 v207, 0x20f40, v37
	v_add_u32_e32 v208, 0x20f80, v37
	v_add_u32_e32 v209, 0x20fc0, v37
	s_addc_u32 s23, s57, s23
	v_mov_b32_e32 v131, v34
	v_mov_b32_e32 v36, s27
	v_mov_b32_e32 v37, s26
	v_cmp_gt_i32_e64 s[56:57], 64, v158
	v_lshlrev_b32_e32 v136, 5, v158
	v_or_b32_e32 v162, 16, v161
	v_or_b32_e32 v172, 32, v161
	v_or_b32_e32 v174, 48, v161
	v_lshl_add_u64 v[176:177], s[22:23], 0, v[130:131]
	v_cndmask_b32_e64 v37, v36, v37, s[56:57]
	v_mov_b32_e32 v36, s25
	v_mov_b32_e32 v130, s24
	v_add_u32_e32 v1, 0, v1
	v_add_u32_e32 v139, 0, v139
	v_add_u32_e32 v137, 0, v137
	v_lshlrev_b32_e32 v140, 1, v140
	v_lshlrev_b32_e32 v143, 5, v161
	v_lshlrev_b32_e32 v144, 5, v162
	v_lshlrev_b32_e32 v145, 5, v172
	v_lshlrev_b32_e32 v146, 5, v174
	v_cndmask_b32_e64 v36, v36, v130, s[56:57]
	v_add_u32_e32 v210, 0x20800, v1
	v_add_u32_e32 v1, 0, v136
	v_ashrrev_i32_e32 v159, 31, v158
	v_mov_b32_e32 v173, v34
	v_mov_b32_e32 v175, v34
	v_lshl_add_u64 v[178:179], v[132:133], 2, v[36:37]
	s_mov_b32 s77, 0
	v_add_u32_e32 v211, v35, v141
	v_add_u32_e32 v212, v142, v138
	v_add_u32_e32 v213, v142, v140
	v_add_u32_e32 v214, s80, v143
	v_add_u32_e32 v215, s80, v144
	v_add_u32_e32 v216, s80, v145
	v_add_u32_e32 v217, s80, v146
	v_add_u32_e32 v218, 0, v135
	v_add_u32_e32 v220, 0x21000, v1
	v_add_u32_e32 v221, s78, v139
	v_add_u32_e32 v232, s79, v137
	v_add_u32_e32 v233, 0, v134
	s_mov_b32 s78, s7
	s_mov_b32 s79, 0
	s_waitcnt vmcnt(0)
	s_branch .LBB0_695
.LBB0_694:
	s_or_b64 exec, exec, s[24:25]
	s_sub_i32 s78, s78, 64
	s_add_i32 s77, s77, 64
	s_cmp_lg_u32 s76, s79
	s_cbranch_scc0 .LBB0_634
	s_waitcnt vmcnt(4)
.LBB0_695:
	v_mov_b32_e32 v1, v158
	s_movk_i32 s23, 0x90
	v_lshrrev_b32_e32 v35, 3, v1
	v_lshlrev_b32_e32 v36, 4, v1
	v_and_b32_e32 v37, 0x70, v36
	s_add_i32 s22, 0, 0x10800
	v_mul_lo_u32 v35, v35, s23
	v_add3_u32 v35, s22, v37, v35
	v_lshrrev_b32_e32 v1, 4, v1
	s_movk_i32 s22, 0x110
	s_nop 0
	ds_write_b128 v35, v[102:105]
	ds_write_b128 v35, v[106:109] offset:9216
	ds_write_b128 v35, v[110:113] offset:18432
	ds_write_b128 v35, v[114:117] offset:27648
	v_and_b32_e32 v35, 0xf0, v36
	v_mul_lo_u32 v1, v1, s22
	v_readlane_b32 s22, v252, 6
	s_nop 1
	v_add3_u32 v1, s22, v35, v1
	ds_write_b128 v1, v[118:121]
	ds_write_b128 v1, v[126:129] offset:8704
	s_and_saveexec_b64 s[22:23], s[36:37]
	ds_write_b128 v210, v[122:125]
	s_or_b64 exec, exec, s[22:23]
	s_add_i32 s79, s79, 1
	s_cmp_lt_u32 s79, s76
	s_cselect_b64 s[22:23], -1, 0
	s_cmp_ge_u32 s79, s76
	s_waitcnt lgkmcnt(0)
	s_barrier
	s_cbranch_scc1 .LBB0_707
	v_mov_b32_e32 v1, v158
	s_mov_b32 s24, s79
	s_lshl_b32 s26, s24, 6
	v_ashrrev_i32_e32 v94, 5, v1
	v_lshlrev_b32_e32 v1, 3, v1
	s_ashr_i32 s25, s26, 31
	v_and_b32_e32 v1, 0xf8, v1
	s_add_u32 s24, s26, s71
	v_lshl_or_b32 v36, v94, 10, v1
	s_addc_u32 s25, s25, s72
	s_sub_i32 s26, s7, s26
	v_mov_b32_e32 v37, v34
	v_mov_b32_e32 v78, 0
	v_mov_b32_e32 v79, v34
	s_min_i32 s80, s26, 64
	v_lshlrev_b64 v[36:37], 1, v[36:37]
	v_mov_b32_e32 v80, v34
	v_mov_b32_e32 v81, v34
	v_mov_b64_e32 v[70:71], v[78:79]
	v_mov_b64_e32 v[74:75], v[78:79]
	v_lshl_add_u64 v[130:131], s[12:13], 0, v[36:37]
	v_lshl_add_u64 v[132:133], s[10:11], 0, v[36:37]
	v_cmp_gt_i32_e32 vcc, s80, v94
	v_mov_b64_e32 v[72:73], v[80:81]
	v_mov_b64_e32 v[76:77], v[80:81]
	s_and_saveexec_b64 s[26:27], vcc
	s_cbranch_execz .LBB0_700
	s_lshl_b64 s[82:83], s[24:25], 11
	v_lshl_add_u64 v[36:37], v[132:133], 0, s[82:83]
	v_lshl_add_u64 v[74:75], v[130:131], 0, s[82:83]
	global_load_dwordx4 v[70:73], v[36:37], off
	s_nop 0
	global_load_dwordx4 v[74:77], v[74:75], off

.LBB0_821:
	s_add_i32 s9, s4, 63
	v_readlane_b32 s14, v255, 27
	s_add_u32 s18, s14, s12
	v_readlane_b32 s14, v253, 32
	s_addc_u32 s19, s14, s13
	v_readlane_b32 s14, v254, 61
	s_add_u32 s20, s14, s12
	v_readlane_b32 s12, v254, 58
	s_addc_u32 s21, s12, s13
	s_lshr_b32 s92, s9, 6
	s_lshl_b32 s9, s96, 9
	s_add_i32 s93, s9, 0
	v_lshl_add_u32 v130, v36, 1, 0
	s_movk_i32 s9, 0x8e
	v_lshl_add_u32 v1, v67, 4, 0
	s_add_i32 s93, s93, 0x13800
	v_mad_i32_i24 v67, v36, s9, v130
	s_lshl_b32 s62, s96, 5
	s_add_i32 s9, s5, 0x7f
	s_cmpk_lt_u32 s9, 0xff
	v_lshlrev_b32_e32 v37, 2, v59
	s_cselect_b64 s[12:13], -1, 0
	v_and_or_b32 v37, v37, 12, s0
	s_ashr_i32 s9, s5, 7
	s_lshl_b32 s14, s8, 1
	s_lshl_b32 s8, s8, 2
	v_lshlrev_b32_e32 v59, 1, v37
	s_and_b32 s16, s14, 2
	v_lshl_or_b32 v37, s9, 4, v95
	s_movk_i32 s14, 0x90
	s_add_i32 s95, s8, 0
	v_mul_lo_u32 v68, v37, s14
	s_add_i32 s14, 0, 0x11400
	s_add_i32 s95, s95, 0x14400
	s_cmpk_gt_i32 s5, 0x7f
	s_cselect_b64 s[38:39], -1, 0
	s_cmpk_gt_i32 s5, 0xff
	s_cselect_b64 s[40:41], -1, 0
	s_cmpk_gt_i32 s5, 0x17f
	s_cselect_b64 s[42:43], -1, 0
	s_cmpk_gt_i32 s5, 0x1ff
	v_lshlrev_b32_e32 v129, 2, v36
	v_lshrrev_b32_e32 v36, 2, v95
	s_cselect_b64 s[44:45], -1, 0
	s_cmp_le_i32 s16, s9
	v_lshlrev_b32_e32 v127, 2, v58
	v_add_u32_e32 v68, s14, v68
	s_movk_i32 s8, 0x110
	v_or_b32_e32 v36, v63, v36
	s_cselect_b64 s[14:15], -1, 0
	s_cmp_lt_i32 s16, s9
	s_mul_i32 s63, s16, 0x1100
	v_mad_u32_u24 v63, v36, s8, 0
	v_lshl_or_b32 v36, s16, 4, v127
	s_cselect_b64 s[16:17], -1, 0
	s_ashr_i32 s97, s75, 31
	s_ashr_i32 s28, s76, 31
	s_ashr_i32 s70, s77, 31
	s_ashr_i32 s25, s78, 31
	s_ashr_i32 s26, s79, 31
	s_ashr_i32 s27, s80, 31
	s_ashr_i32 s29, s81, 31
	s_ashr_i32 s30, s82, 31
	s_ashr_i32 s31, s83, 31
	s_ashr_i32 s34, s84, 31
	s_ashr_i32 s35, s85, 31
	s_ashr_i32 s71, s86, 31
	s_ashr_i32 s73, s87, 31
	s_ashr_i32 s23, s88, 31
	s_ashr_i32 s22, s89, 31
	s_lshl_b64 s[0:1], s[0:1], 1
	v_cmp_eq_u32_e64 s[36:37], 0, v58
	v_mul_lo_u32 v58, v83, s8
	v_mul_lo_u32 v69, v118, s8
	v_or_b32_e32 v70, 2, v36
	s_add_u32 s8, s20, s0
	s_mul_i32 s64, s9, 0x1100
	v_cmp_gt_i32_e64 s[50:51], v70, v37
	v_or_b32_e32 v70, 3, v36
	v_or_b32_e32 v72, 17, v36
	s_addc_u32 s9, s21, s1
	v_cmp_gt_i32_e64 s[46:47], v36, v37
	v_cmp_lt_i32_e64 s[48:49], v36, v37
	v_cmp_gt_i32_e64 s[52:53], v70, v37
	v_lshlrev_b32_e32 v70, 1, v36
	v_or_b32_e32 v71, 16, v36
	v_cmp_gt_i32_e64 s[56:57], v72, v37
	v_or_b32_e32 v72, 18, v36
	v_or_b32_e32 v36, 19, v36
	s_add_u32 s0, s18, s0
	v_lshl_add_u32 v35, v95, 4, 0
	v_add_u32_e32 v66, 0, v66
	v_add_u32_e32 v65, 0, v65
	v_add_u32_e32 v64, 0, v64
	v_cmp_gt_i32_e64 s[54:55], v71, v37
	v_cmp_gt_i32_e64 s[58:59], v72, v37
	v_cmp_gt_i32_e64 s[60:61], v36, v37
	v_lshlrev_b32_e32 v71, 1, v71
	v_or_b32_e32 v94, 16, v95
	v_or_b32_e32 v96, 32, v95
	v_or_b32_e32 v98, 48, v95
	v_lshlrev_b32_e32 v36, 1, v127
	v_mov_b32_e32 v37, v34
	s_addc_u32 s1, s19, s1
	v_add_u32_e32 v132, 0x14000, v64
	s_mov_b32 s94, 0
	v_add_u32_e32 v133, 0x14200, v64
	s_mulk_i32 s96, 0x1100
	v_add_u32_e32 v135, 0x14040, v64
	v_add_u32_e32 v136, 0x14080, v64
	v_add_u32_e32 v137, 0x140c0, v64
	v_add_u32_e32 v138, 0x14100, v64
	v_add_u32_e32 v139, 0x14140, v64
	v_add_u32_e32 v140, 0x14180, v64
	v_add_u32_e32 v141, 0x141c0, v64
	v_lshlrev_b32_e32 v142, 5, v95
	v_lshlrev_b32_e32 v143, 5, v94
	v_mov_b32_e32 v97, v34
	v_lshlrev_b32_e32 v145, 5, v96
	v_mov_b32_e32 v99, v34
	v_lshlrev_b32_e32 v146, 5, v98
	v_add_u32_e32 v148, 0x14240, v64
	v_add_u32_e32 v149, 0x14280, v64
	v_add_u32_e32 v150, 0x142c0, v64
	v_add_u32_e32 v151, 0x14300, v64
	v_add_u32_e32 v152, 0x14340, v64
	v_add_u32_e32 v153, 0x14380, v64
	v_add_u32_e32 v154, 0x143c0, v64
	v_lshl_add_u64 v[100:101], s[8:9], 0, v[36:37]
	v_lshl_add_u64 v[102:103], s[0:1], 0, v[36:37]
	s_mov_b32 s8, 64
	v_add_u32_e32 v156, v1, v58
	v_add_u32_e32 v157, v35, v69
	v_add_u32_e32 v158, s62, v67
	v_add_u32_e32 v159, v63, v59
	v_add_u32_e32 v160, v68, v70
	v_add_u32_e32 v161, v68, v71
	v_add_u32_e32 v162, 0, v60
	v_add_u32_e32 v163, 0, v62
	v_add_u32_e32 v172, s63, v66
	v_add_u32_e32 v173, s64, v65
	v_add_u32_e32 v174, 0, v61
	s_mov_b32 s9, s4
	s_waitcnt vmcnt(0)
	s_branch .LBB0_823

.LBB0_823:
	s_waitcnt lgkmcnt(0)
	v_add_f32_e32 v1, 0, v91
	v_add_f32_e32 v1, v120, v1
	v_add_f32_e32 v1, v121, v1
	v_add_f32_e32 v1, v122, v1
	v_add_f32_e32 v1, v123, v1
	v_add_f32_e32 v1, v124, v1
	v_add_f32_e32 v1, v125, v1
	v_add_f32_e32 v1, v126, v1
	v_add_f32_e32 v1, v128, v1
	v_add_f32_e32 v1, v131, v1
	v_add_f32_e32 v1, v134, v1
	v_add_f32_e32 v1, v144, v1
	v_add_f32_e32 v1, v147, v1
	v_add_f32_e32 v1, v155, v1
	v_add_f32_e32 v1, v175, v1
	v_add_f32_e32 v1, v176, v1
	v_add_u32_e32 v35, s93, v129
	ds_write_b128 v156, v[42:45]
	ds_write_b128 v156, v[46:49] offset:8704
	ds_write_b128 v157, v[50:53] offset:53248
	ds_write_b128 v157, v[54:57] offset:61952
	ds_write_b32 v35, v1
	v_add_u32_e32 v35, 0, v129
	v_add_u32_e32 v1, 0x13800, v35
	s_waitcnt lgkmcnt(0)
	s_barrier
	ds_read2st64_b32 v[36:37], v1 offset1:2
	ds_read2st64_b32 v[58:59], v1 offset0:4 offset1:6
	s_andn2_b64 vcc, exec, s[12:13]
	s_waitcnt lgkmcnt(1)
	v_add_f32_e32 v60, 0, v36
	v_cndmask_b32_e64 v61, 0, v37, s[40:41]
	v_cndmask_b32_e64 v36, 0, v60, s[38:39]
	s_waitcnt lgkmcnt(0)
	v_cndmask_b32_e64 v1, 0, v58, s[42:43]
	v_add_f32_e32 v36, v36, v61
	v_cndmask_b32_e64 v62, 0, v59, s[44:45]
	v_add_f32_e32 v1, v36, v1
	v_add_f32_e32 v61, v1, v62
	v_mov_b32_e32 v90, v37
	v_pk_add_f32 v[36:37], v[60:61], v[90:91]
	s_nop 0
	v_add_f32_e32 v1, v36, v58
	v_add_f32_e32 v59, v1, v59
	v_sub_f32_e32 v1, v59, v36
	v_mul_f32_e32 v1, 0x3fb8aa3b, v1
	v_exp_f32_e32 v58, v1
	v_add_u32_e32 v1, s96, v130
	ds_read_u16 v184, v1
	s_nop 0
	v_sub_f32_e32 v62, v37, v36
	v_mul_f32_e32 v62, 0x3fb8aa3b, v62
	v_exp_f32_e32 v63, v62
	v_sub_f32_e32 v62, v36, v37
	s_waitcnt lgkmcnt(1)
	s_waitcnt lgkmcnt(0)
	v_lshlrev_b32_e32 v61, 16, v184
	v_add_f32_e32 v64, v120, v37
	v_mul_f32_e32 v61, v63, v61
	v_cvt_pk_bf16_f32 v61, v61, s0
	s_mul_i32 s0, s76, 0x110
	v_add_u32_e32 v37, s0, v130
	ds_read_u16 v184, v37
	ds_read_u16 v188, v37 offset:272
	ds_read_u16 v192, v37 offset:544
	ds_read_u16 v196, v37 offset:816
	ds_read_u16 v200, v37 offset:1088
	ds_read_u16 v204, v37 offset:1360
	ds_write_b16 v1, v61
	s_nop 0
	v_sub_f32_e32 v63, v64, v36
	v_mul_f32_e32 v63, 0x3fb8aa3b, v63
	v_mul_f32_e32 v60, 0x3fb8aa3b, v91
	v_exp_f32_e32 v66, v63
	s_waitcnt lgkmcnt(6)
	v_lshlrev_b32_e32 v65, 16, v184
	ds_read_u16 v184, v37 offset:1632
	v_mul_f32_e32 v61, 0x3fb8aa3b, v120
	v_sub_f32_e32 v63, v36, v64
	v_exp_f32_e32 v60, v60
	v_mul_f32_e32 v62, 0x3fb8aa3b, v62
	v_exp_f32_e32 v61, v61
	v_mul_f32_e32 v63, 0x3fb8aa3b, v63
	v_exp_f32_e32 v62, v62
	v_exp_f32_e32 v63, v63
	v_pk_add_f32 v[60:61], v[60:61], 1.0 op_sel_hi:[1,0] neg_lo:[1,0] neg_hi:[1,0]
	v_mul_f32_e32 v65, v66, v65
	v_cvt_pk_bf16_f32 v65, v65, s0
	v_pk_mul_f32 v[62:63], v[60:61], v[62:63]
	ds_write_b16 v37, v65
	v_cvt_pk_bf16_f32 v60, v62, s0
	ds_write_b16 v1, v60 offset:17408
	v_cvt_pk_bf16_f32 v1, v63, s0
	ds_write_b16 v37, v1 offset:17408
	v_add_f32_e32 v1, v121, v64
	v_pk_mul_f32 v[60:61], v[58:59], v[62:63] op_sel_hi:[0,1]
	s_nop 0
	v_sub_f32_e32 v64, v1, v36
	v_mul_f32_e32 v64, 0x3fb8aa3b, v64
	v_exp_f32_e32 v65, v64
	v_sub_f32_e32 v64, v36, v1
	s_waitcnt lgkmcnt(9)
	v_lshlrev_b32_e32 v63, 16, v188
	ds_read_u16 v188, v37 offset:1904
	v_add_f32_e32 v1, v122, v1
	v_mul_f32_e32 v63, v65, v63
	v_cvt_pk_bf16_f32 v63, v63, s0
	ds_write_b16 v37, v63 offset:272
	s_nop 0
	v_sub_f32_e32 v65, v1, v36
	v_mul_f32_e32 v65, 0x3fb8aa3b, v65
	v_mul_f32_e32 v62, 0x3fb8aa3b, v121
	v_exp_f32_e32 v67, v65
	s_waitcnt lgkmcnt(10)
	v_lshlrev_b32_e32 v66, 16, v192
	ds_read_u16 v192, v37 offset:2176
	v_mul_f32_e32 v63, 0x3fb8aa3b, v122
	v_sub_f32_e32 v65, v36, v1
	v_exp_f32_e32 v62, v62
	v_mul_f32_e32 v64, 0x3fb8aa3b, v64
	v_exp_f32_e32 v63, v63
	v_mul_f32_e32 v65, 0x3fb8aa3b, v65
	v_exp_f32_e32 v64, v64
	v_exp_f32_e32 v65, v65
	v_pk_add_f32 v[62:63], v[62:63], 1.0 op_sel_hi:[1,0] neg_lo:[1,0] neg_hi:[1,0]
	v_mul_f32_e32 v66, v67, v66
	v_cvt_pk_bf16_f32 v66, v66, s0
	v_pk_mul_f32 v[64:65], v[62:63], v[64:65]
	v_add_f32_e32 v1, v123, v1
	v_cvt_pk_bf16_f32 v62, v64, s0
	ds_write_b16 v37, v62 offset:17680
	v_pk_mul_f32 v[62:63], v[58:59], v[64:65] op_sel_hi:[0,1]
	v_cvt_pk_bf16_f32 v64, v65, s0
	ds_write_b16 v37, v66 offset:544
	ds_write_b16 v37, v64 offset:17952
	s_nop 0
	v_sub_f32_e32 v66, v1, v36
	v_mul_f32_e32 v66, 0x3fb8aa3b, v66
	v_exp_f32_e32 v67, v66
	v_sub_f32_e32 v66, v36, v1
	s_waitcnt lgkmcnt(13)
	v_lshlrev_b32_e32 v65, 16, v196
	ds_read_u16 v196, v37 offset:2448
	v_add_f32_e32 v1, v124, v1
	v_mul_f32_e32 v65, v67, v65
	v_cvt_pk_bf16_f32 v65, v65, s0
	ds_write_b16 v37, v65 offset:816
	s_nop 0
	v_sub_f32_e32 v67, v1, v36
	v_mul_f32_e32 v67, 0x3fb8aa3b, v67
	v_mul_f32_e32 v64, 0x3fb8aa3b, v123
	v_exp_f32_e32 v69, v67
	s_waitcnt lgkmcnt(14)
	v_lshlrev_b32_e32 v68, 16, v200
	ds_read_u16 v200, v37 offset:2720
	v_mul_f32_e32 v65, 0x3fb8aa3b, v124
	v_sub_f32_e32 v67, v36, v1
	v_exp_f32_e32 v64, v64
	v_mul_f32_e32 v66, 0x3fb8aa3b, v66
	v_exp_f32_e32 v65, v65
	v_mul_f32_e32 v67, 0x3fb8aa3b, v67
	v_exp_f32_e32 v66, v66
	v_exp_f32_e32 v67, v67
	v_pk_add_f32 v[64:65], v[64:65], 1.0 op_sel_hi:[1,0] neg_lo:[1,0] neg_hi:[1,0]
	v_mul_f32_e32 v68, v69, v68
	v_cvt_pk_bf16_f32 v68, v68, s0
	v_pk_mul_f32 v[66:67], v[64:65], v[66:67]
	v_add_f32_e32 v1, v125, v1
	v_cvt_pk_bf16_f32 v64, v66, s0
	ds_write_b16 v37, v64 offset:18224
	v_pk_mul_f32 v[64:65], v[58:59], v[66:67] op_sel_hi:[0,1]
	v_cvt_pk_bf16_f32 v66, v67, s0
	ds_write_b16 v37, v68 offset:1088
	ds_write_b16 v37, v66 offset:18496
	s_nop 0
	v_sub_f32_e32 v68, v1, v36
	v_mul_f32_e32 v68, 0x3fb8aa3b, v68
	v_exp_f32_e32 v69, v68
	v_sub_f32_e32 v68, v36, v1
	s_waitcnt lgkmcnt(15)
	v_lshlrev_b32_e32 v67, 16, v204
	ds_read_u16 v204, v37 offset:2992
	v_add_f32_e32 v1, v126, v1
	v_mul_f32_e32 v67, v69, v67
	v_cvt_pk_bf16_f32 v67, v67, s0
	ds_write_b16 v37, v67 offset:1360
	s_nop 0
	v_sub_f32_e32 v69, v1, v36
	v_mul_f32_e32 v69, 0x3fb8aa3b, v69
	v_mul_f32_e32 v66, 0x3fb8aa3b, v125
	v_exp_f32_e32 v71, v69
	s_waitcnt lgkmcnt(15)
	v_lshlrev_b32_e32 v70, 16, v184
	ds_read_u16 v184, v37 offset:3264
	v_mul_f32_e32 v67, 0x3fb8aa3b, v126
	v_sub_f32_e32 v69, v36, v1
	v_exp_f32_e32 v66, v66
	v_mul_f32_e32 v68, 0x3fb8aa3b, v68
	v_exp_f32_e32 v67, v67
	v_mul_f32_e32 v69, 0x3fb8aa3b, v69
	v_exp_f32_e32 v68, v68
	v_exp_f32_e32 v69, v69
	v_pk_add_f32 v[66:67], v[66:67], 1.0 op_sel_hi:[1,0] neg_lo:[1,0] neg_hi:[1,0]
	v_mul_f32_e32 v70, v71, v70
	v_cvt_pk_bf16_f32 v70, v70, s0
	v_pk_mul_f32 v[66:67], v[66:67], v[68:69]
	v_cvt_pk_bf16_f32 v60, v60, v61
	v_cvt_pk_bf16_f32 v68, v66, s0
	ds_write_b16 v37, v68 offset:18768
	v_pk_mul_f32 v[68:69], v[58:59], v[66:67] op_sel_hi:[0,1]
	v_cvt_pk_bf16_f32 v66, v67, s0
	v_cvt_pk_bf16_f32 v61, v62, v63
	v_cvt_pk_bf16_f32 v62, v64, v65
	v_cvt_pk_bf16_f32 v63, v68, v69
	ds_write_b16 v37, v70 offset:1632
	ds_write_b16 v37, v66 offset:19040
	ds_write_b128 v158, v[60:63] offset:34816
	v_add_f32_e32 v1, v128, v1
	s_nop 0
	v_sub_f32_e32 v62, v1, v36
	v_mul_f32_e32 v62, 0x3fb8aa3b, v62
	v_exp_f32_e32 v63, v62
	v_sub_f32_e32 v62, v36, v1
	s_waitcnt lgkmcnt(15)
	v_lshlrev_b32_e32 v61, 16, v188
	ds_read_u16 v188, v37 offset:3536
	v_add_f32_e32 v1, v131, v1
	v_mul_f32_e32 v61, v63, v61
	v_cvt_pk_bf16_f32 v61, v61, s0
	ds_write_b16 v37, v61 offset:1904
	s_nop 0
	v_sub_f32_e32 v63, v1, v36
	v_mul_f32_e32 v63, 0x3fb8aa3b, v63
	v_mul_f32_e32 v60, 0x3fb8aa3b, v128
	v_exp_f32_e32 v65, v63
	s_waitcnt lgkmcnt(15)
	v_lshlrev_b32_e32 v64, 16, v192
	ds_read_u16 v192, v37 offset:3808
	v_mul_f32_e32 v61, 0x3fb8aa3b, v131
	v_sub_f32_e32 v63, v36, v1
	v_exp_f32_e32 v60, v60
	v_mul_f32_e32 v62, 0x3fb8aa3b, v62
	v_exp_f32_e32 v61, v61
	v_mul_f32_e32 v63, 0x3fb8aa3b, v63
	v_exp_f32_e32 v62, v62
	v_exp_f32_e32 v63, v63
	v_pk_add_f32 v[60:61], v[60:61], 1.0 op_sel_hi:[1,0] neg_lo:[1,0] neg_hi:[1,0]
	v_mul_f32_e32 v64, v65, v64
	v_cvt_pk_bf16_f32 v64, v64, s0
	v_pk_mul_f32 v[62:63], v[60:61], v[62:63]
	v_add_f32_e32 v1, v134, v1
	v_cvt_pk_bf16_f32 v60, v62, s0
	ds_write_b16 v37, v60 offset:19312
	v_pk_mul_f32 v[60:61], v[58:59], v[62:63] op_sel_hi:[0,1]
	v_cvt_pk_bf16_f32 v62, v63, s0
	ds_write_b16 v37, v64 offset:2176
	ds_write_b16 v37, v62 offset:19584
	s_nop 0
	v_sub_f32_e32 v64, v1, v36
	v_mul_f32_e32 v64, 0x3fb8aa3b, v64
	v_exp_f32_e32 v65, v64
	v_sub_f32_e32 v64, v36, v1
	s_waitcnt lgkmcnt(15)
	v_lshlrev_b32_e32 v63, 16, v196
	v_add_f32_e32 v1, v144, v1
	v_mul_f32_e32 v63, v65, v63
	v_cvt_pk_bf16_f32 v63, v63, s0
	ds_write_b16 v37, v63 offset:2448
	s_nop 0
	v_sub_f32_e32 v65, v1, v36
	v_mul_f32_e32 v65, 0x3fb8aa3b, v65
	v_mul_f32_e32 v62, 0x3fb8aa3b, v134
	v_exp_f32_e32 v67, v65
	s_waitcnt lgkmcnt(15)
	v_lshlrev_b32_e32 v66, 16, v200
	v_mul_f32_e32 v63, 0x3fb8aa3b, v144
	v_sub_f32_e32 v65, v36, v1
	v_exp_f32_e32 v62, v62
	v_mul_f32_e32 v64, 0x3fb8aa3b, v64
	v_exp_f32_e32 v63, v63
	v_mul_f32_e32 v65, 0x3fb8aa3b, v65
	v_exp_f32_e32 v64, v64
	v_exp_f32_e32 v65, v65
	v_pk_add_f32 v[62:63], v[62:63], 1.0 op_sel_hi:[1,0] neg_lo:[1,0] neg_hi:[1,0]
	v_mul_f32_e32 v66, v67, v66
	v_cvt_pk_bf16_f32 v66, v66, s0
	v_pk_mul_f32 v[64:65], v[62:63], v[64:65]
	v_add_f32_e32 v1, v147, v1
	v_cvt_pk_bf16_f32 v62, v64, s0
	ds_write_b16 v37, v62 offset:19856
	v_pk_mul_f32 v[62:63], v[58:59], v[64:65] op_sel_hi:[0,1]
	v_cvt_pk_bf16_f32 v64, v65, s0
	ds_write_b16 v37, v66 offset:2720
	ds_write_b16 v37, v64 offset:20128
	s_nop 0
	v_sub_f32_e32 v66, v1, v36
	v_mul_f32_e32 v66, 0x3fb8aa3b, v66
	v_exp_f32_e32 v67, v66
	v_sub_f32_e32 v66, v36, v1
	s_waitcnt lgkmcnt(15)
	v_lshlrev_b32_e32 v65, 16, v204
	v_add_f32_e32 v1, v155, v1
	v_mul_f32_e32 v65, v67, v65
	v_cvt_pk_bf16_f32 v65, v65, s0
	ds_write_b16 v37, v65 offset:2992
	s_nop 0
	v_sub_f32_e32 v67, v1, v36
	v_mul_f32_e32 v67, 0x3fb8aa3b, v67
	v_mul_f32_e32 v64, 0x3fb8aa3b, v147
	v_exp_f32_e32 v69, v67
	s_waitcnt lgkmcnt(15)
	v_lshlrev_b32_e32 v68, 16, v184
	v_mul_f32_e32 v65, 0x3fb8aa3b, v155
	v_sub_f32_e32 v67, v36, v1
	v_exp_f32_e32 v64, v64
	v_mul_f32_e32 v66, 0x3fb8aa3b, v66
	v_exp_f32_e32 v65, v65
	v_mul_f32_e32 v67, 0x3fb8aa3b, v67
	v_exp_f32_e32 v66, v66
	v_exp_f32_e32 v67, v67
	v_pk_add_f32 v[64:65], v[64:65], 1.0 op_sel_hi:[1,0] neg_lo:[1,0] neg_hi:[1,0]
	v_mul_f32_e32 v68, v69, v68
	v_cvt_pk_bf16_f32 v68, v68, s0
	v_pk_mul_f32 v[66:67], v[64:65], v[66:67]
	v_add_f32_e32 v1, v175, v1
	v_cvt_pk_bf16_f32 v64, v66, s0
	ds_write_b16 v37, v64 offset:20400
	v_pk_mul_f32 v[64:65], v[58:59], v[66:67] op_sel_hi:[0,1]
	v_cvt_pk_bf16_f32 v66, v67, s0
	ds_write_b16 v37, v68 offset:3264
	ds_write_b16 v37, v66 offset:20672
	s_nop 0
	v_sub_f32_e32 v68, v1, v36
	v_mul_f32_e32 v68, 0x3fb8aa3b, v68
	v_exp_f32_e32 v69, v68
	v_sub_f32_e32 v68, v36, v1
	s_waitcnt lgkmcnt(13)
	v_lshlrev_b32_e32 v67, 16, v188
	v_add_f32_e32 v1, v176, v1
	v_mul_f32_e32 v67, v69, v67
	v_cvt_pk_bf16_f32 v67, v67, s0
	ds_write_b16 v37, v67 offset:3536
	s_nop 0
	v_sub_f32_e32 v69, v1, v36
	v_mul_f32_e32 v66, 0x3fb8aa3b, v175
	v_mul_f32_e32 v69, 0x3fb8aa3b, v69
	v_sub_f32_e32 v1, v36, v1
	s_waitcnt lgkmcnt(12)
	v_lshlrev_b32_e32 v70, 16, v192
	v_mul_f32_e32 v67, 0x3fb8aa3b, v176
	v_exp_f32_e32 v66, v66
	v_mul_f32_e32 v68, 0x3fb8aa3b, v68
	v_exp_f32_e32 v67, v67
	v_exp_f32_e32 v71, v69
	v_mul_f32_e32 v1, 0x3fb8aa3b, v1
	v_exp_f32_e32 v68, v68
	v_exp_f32_e32 v69, v1
	v_mul_f32_e32 v1, v71, v70
	v_pk_add_f32 v[66:67], v[66:67], 1.0 op_sel_hi:[1,0] neg_lo:[1,0] neg_hi:[1,0]
	v_cvt_pk_bf16_f32 v1, v1, s0
	v_pk_mul_f32 v[66:67], v[66:67], v[68:69]
	ds_write_b16 v37, v1 offset:3808
	v_cvt_pk_bf16_f32 v1, v66, s0
	v_pk_mul_f32 v[68:69], v[58:59], v[66:67] op_sel_hi:[0,1]
	ds_write_b16 v37, v1 offset:20944
	v_cvt_pk_bf16_f32 v1, v67, s0
	v_cvt_pk_bf16_f32 v60, v60, v61
	v_cvt_pk_bf16_f32 v61, v62, v63
	v_cvt_pk_bf16_f32 v62, v64, v65
	v_cvt_pk_bf16_f32 v63, v68, v69
	ds_write_b16 v37, v1 offset:21216
	ds_write_b128 v158, v[60:63] offset:34832
	s_cbranch_vccnz .LBB0_825
	v_mul_f32_e32 v1, 0x3fb8aa3b, v36
	v_exp_f32_e32 v1, v1
	v_mul_f32_e32 v36, 0x3fb8aa3b, v59
	v_exp_f32_e32 v36, v36
	v_add_u32_e32 v37, 0x14000, v35
	ds_write_b32 v37, v1
	v_add_u32_e32 v1, 0x14200, v35
	ds_write_b32 v1, v36

.LBB0_873:
	ds_read_b128 v[184:187], v133
	ds_read_b128 v[188:191], v163
	ds_read_b128 v[192:195], v163 offset:64
	ds_read_b128 v[196:199], v148
	ds_read_b128 v[200:203], v163 offset:2304
	ds_read_b128 v[204:207], v163 offset:2368
	s_nop 0
	s_waitcnt lgkmcnt(6)
	s_waitcnt lgkmcnt(5)
	v_pk_mul_f32 v[4:5], v[4:5], v[186:187]
	ds_read_b128 v[208:211], v149
	v_pk_mul_f32 v[2:3], v[2:3], v[184:185]
	s_nop 0
	s_waitcnt lgkmcnt(5)
	v_mfma_f32_16x16x32_bf16 v[2:5], v[188:191], v[62:65], v[2:5]
	ds_read_b128 v[184:187], v163 offset:4608
	s_nop 0
	s_waitcnt lgkmcnt(5)
	v_mfma_f32_16x16x32_bf16 v[2:5], v[192:195], v[58:61], v[2:5]
	ds_read_b128 v[188:191], v163 offset:4672
	s_nop 0
	s_waitcnt lgkmcnt(5)
	v_pk_mul_f32 v[12:13], v[12:13], v[198:199]
	ds_read_b128 v[192:195], v150
	v_pk_mul_f32 v[10:11], v[10:11], v[196:197]
	s_nop 0
	s_waitcnt lgkmcnt(5)
	v_mfma_f32_16x16x32_bf16 v[10:13], v[200:203], v[62:65], v[10:13]
	ds_read_b128 v[196:199], v163 offset:6912
	s_nop 0
	s_waitcnt lgkmcnt(5)
	v_mfma_f32_16x16x32_bf16 v[10:13], v[204:207], v[58:61], v[10:13]
	ds_read_b128 v[200:203], v163 offset:6976
	s_nop 0
	s_waitcnt lgkmcnt(5)
	v_pk_mul_f32 v[8:9], v[8:9], v[210:211]
	ds_read_b128 v[204:207], v151
	v_pk_mul_f32 v[6:7], v[6:7], v[208:209]
	s_nop 0
	s_waitcnt lgkmcnt(5)
	v_mfma_f32_16x16x32_bf16 v[6:9], v[184:187], v[62:65], v[6:9]
	ds_read_b128 v[184:187], v163 offset:9216
	s_nop 0
	s_waitcnt lgkmcnt(5)
	v_mfma_f32_16x16x32_bf16 v[6:9], v[188:191], v[58:61], v[6:9]
	ds_read_b128 v[188:191], v163 offset:9280
	s_nop 0
	s_waitcnt lgkmcnt(5)
	v_pk_mul_f32 v[16:17], v[16:17], v[194:195]
	ds_read_b128 v[208:211], v152
	v_pk_mul_f32 v[14:15], v[14:15], v[192:193]
	s_nop 0
	s_waitcnt lgkmcnt(5)
	v_mfma_f32_16x16x32_bf16 v[14:17], v[196:199], v[62:65], v[14:17]
	ds_read_b128 v[192:195], v163 offset:11520
	s_nop 0
	s_waitcnt lgkmcnt(5)
	v_mfma_f32_16x16x32_bf16 v[14:17], v[200:203], v[58:61], v[14:17]
	ds_read_b128 v[196:199], v163 offset:11584
	s_nop 0
	s_waitcnt lgkmcnt(5)
	v_pk_mul_f32 v[20:21], v[20:21], v[206:207]
	ds_read_b128 v[200:203], v153
	v_pk_mul_f32 v[18:19], v[18:19], v[204:205]
	s_nop 0
	s_waitcnt lgkmcnt(5)
	v_mfma_f32_16x16x32_bf16 v[18:21], v[184:187], v[62:65], v[18:21]
	ds_read_b128 v[184:187], v163 offset:13824
	s_nop 0
	s_waitcnt lgkmcnt(5)
	v_mfma_f32_16x16x32_bf16 v[18:21], v[188:191], v[58:61], v[18:21]
	ds_read_b128 v[188:191], v163 offset:13888
	s_nop 0
	s_waitcnt lgkmcnt(5)
	v_pk_mul_f32 v[24:25], v[24:25], v[210:211]
	ds_read_b128 v[204:207], v154
	v_pk_mul_f32 v[22:23], v[22:23], v[208:209]
	s_nop 0
	s_waitcnt lgkmcnt(5)
	v_mfma_f32_16x16x32_bf16 v[22:25], v[192:195], v[62:65], v[22:25]
	s_nop 0
	s_waitcnt lgkmcnt(4)
	v_mfma_f32_16x16x32_bf16 v[22:25], v[196:199], v[58:61], v[22:25]
	s_nop 0
	s_waitcnt lgkmcnt(3)
	v_pk_mul_f32 v[28:29], v[28:29], v[202:203]
	v_pk_mul_f32 v[26:27], v[26:27], v[200:201]
	s_nop 0
	s_waitcnt lgkmcnt(2)
	v_mfma_f32_16x16x32_bf16 v[26:29], v[184:187], v[62:65], v[26:29]
	s_nop 0
	s_waitcnt lgkmcnt(1)
	v_mfma_f32_16x16x32_bf16 v[26:29], v[188:191], v[58:61], v[26:29]
	s_nop 0
	s_waitcnt lgkmcnt(0)
	v_pk_mul_f32 v[32:33], v[32:33], v[206:207]
	v_pk_mul_f32 v[30:31], v[30:31], v[204:205]
	ds_read_b128 v[178:181], v163 offset:16128
	s_waitcnt lgkmcnt(0)
	v_mfma_f32_16x16x32_bf16 v[30:33], v[178:181], v[62:65], v[30:33]
	ds_read_b128 v[62:65], v163 offset:16192
	s_waitcnt lgkmcnt(0)
	s_barrier
	v_mfma_f32_16x16x32_bf16 v[30:33], v[62:65], v[58:61], v[30:33]
	s_waitcnt vmcnt(0)
	s_and_saveexec_b64 s[20:21], s[68:69]
	s_cbranch_execz .LBB0_875
	v_add_u32_e32 v1, 0, v142
	v_add_u32_e32 v1, 0x14400, v1
	ds_read_b128 v[58:61], v1
	ds_read_b128 v[62:65], v1 offset:16
	s_mov_b32 s0, 0xf800000
	s_waitcnt lgkmcnt(0)
	v_mov_b32_e32 v178, v58
	v_mov_b32_e32 v179, v62
	v_mov_b32_e32 v62, v59
	v_pk_add_f32 v[58:59], v[178:179], v[62:63]
	v_mov_b32_e32 v62, v60
	v_mov_b32_e32 v63, v64
	v_mov_b32_e32 v64, v61
	v_pk_add_f32 v[60:61], v[62:63], v[64:65]
	s_waitcnt vmcnt(0)
	v_lshlrev_b32_e32 v62, 16, v37
	v_pk_add_f32 v[58:59], v[58:59], v[60:61]
	v_and_b32_e32 v63, 0xffff0000, v37
	v_add_f32_e32 v1, v58, v59
	v_fmamk_f32 v1, v1, 0x3c000000, v222
	v_cmp_gt_f32_e32 vcc, s0, v1
	v_mul_f32_e32 v35, 0x4f800000, v1
	s_nop 0
	v_cndmask_b32_e32 v1, v1, v35, vcc
	v_sqrt_f32_e32 v35, v1
	s_nop 0
	v_add_u32_e32 v58, -1, v35
	v_fma_f32 v59, -v58, v35, v1
	v_cmp_ge_f32_e64 s[0:1], 0, v59
	v_add_u32_e32 v59, 1, v35
	s_nop 0
	v_cndmask_b32_e64 v58, v35, v58, s[0:1]
	v_fma_f32 v35, -v59, v35, v1
	v_cmp_lt_f32_e64 s[0:1], 0, v35
	s_nop 1
	v_cndmask_b32_e64 v35, v58, v59, s[0:1]
	v_mul_f32_e32 v58, 0x37800000, v35
	v_cndmask_b32_e32 v35, v35, v58, vcc
	v_cmp_class_f32_e32 vcc, v1, v223
	s_nop 1
	v_cndmask_b32_e32 v1, v35, v1, vcc
	v_div_scale_f32 v35, s[0:1], v1, v1, 1.0
	v_rcp_f32_e32 v58, v35
	s_movk_i32 s0, 0x3000
	v_fma_f32 v59, -v35, v58, 1.0
	v_fmac_f32_e32 v58, v59, v58
	v_div_scale_f32 v59, vcc, 1.0, v1, 1.0
	v_mul_f32_e32 v60, v59, v58
	v_fma_f32 v61, -v35, v60, v59
	v_fmac_f32_e32 v60, v61, v58
	v_fma_f32 v35, -v35, v60, v59
	v_div_fmas_f32 v35, v35, v58, v60
	v_div_fixup_f32 v58, v35, v1, 1.0
	v_pk_mul_f32 v[60:61], v[80:81], v[58:59] op_sel_hi:[1,0]
	v_pk_mul_f32 v[58:59], v[78:79], v[58:59] op_sel_hi:[1,0]
	v_pk_mul_f32 v[60:61], v[40:41], v[60:61]
	v_pk_mul_f32 v[58:59], v[38:39], v[58:59]
	v_pk_mul_f32 v[60:61], v[60:61], v[62:63]
	s_nop 0
	v_cvt_pk_bf16_f32 v37, v60, v61
	v_lshlrev_b32_e32 v60, 16, v36
	v_and_b32_e32 v61, 0xffff0000, v36
	v_pk_mul_f32 v[58:59], v[58:59], v[60:61]
	s_nop 0
	v_cvt_pk_bf16_f32 v36, v58, v59
	v_mad_u64_u32 v[58:59], s[0:1], v116, s0, v[100:101]
	v_mad_i32_i24 v59, s19, v230, v59
	global_store_dwordx2 v[58:59], v[36:37], off

.LBB0_878:
	v_add_u32_e32 v1, 0, v143
	v_add_u32_e32 v1, 0x14400, v1
	ds_read_b128 v[58:61], v1
	ds_read_b128 v[62:65], v1 offset:16
	s_mov_b32 s0, 0xf800000
	s_waitcnt lgkmcnt(0)
	v_mov_b32_e32 v36, v58
	v_mov_b32_e32 v37, v62
	v_mov_b32_e32 v62, v59
	v_mov_b32_e32 v58, v60
	v_mov_b32_e32 v59, v64
	v_mov_b32_e32 v64, v61
	v_pk_add_f32 v[36:37], v[36:37], v[62:63]
	v_pk_add_f32 v[58:59], v[58:59], v[64:65]
	v_lshlrev_b32_e32 v60, 16, v115
	v_pk_add_f32 v[36:37], v[36:37], v[58:59]
	v_and_b32_e32 v61, 0xffff0000, v115
	v_add_f32_e32 v1, v36, v37
	v_fmamk_f32 v1, v1, 0x3c000000, v222
	v_cmp_gt_f32_e32 vcc, s0, v1
	v_mul_f32_e32 v35, 0x4f800000, v1
	s_nop 0
	v_cndmask_b32_e32 v1, v1, v35, vcc
	v_sqrt_f32_e32 v35, v1
	s_nop 0
	v_add_u32_e32 v36, -1, v35
	v_fma_f32 v37, -v36, v35, v1
	v_cmp_ge_f32_e64 s[0:1], 0, v37
	v_add_u32_e32 v37, 1, v35
	s_nop 0
	v_cndmask_b32_e64 v36, v35, v36, s[0:1]
	v_fma_f32 v35, -v37, v35, v1
	v_cmp_lt_f32_e64 s[0:1], 0, v35
	s_nop 1
	v_cndmask_b32_e64 v35, v36, v37, s[0:1]
	v_mul_f32_e32 v36, 0x37800000, v35
	v_cndmask_b32_e32 v35, v35, v36, vcc
	v_cmp_class_f32_e32 vcc, v1, v223
	s_nop 1
	v_cndmask_b32_e32 v1, v35, v1, vcc
	v_div_scale_f32 v35, s[0:1], v1, v1, 1.0
	v_rcp_f32_e32 v36, v35
	s_movk_i32 s0, 0x3000
	v_fma_f32 v37, -v35, v36, 1.0
	v_fmac_f32_e32 v36, v37, v36
	v_div_scale_f32 v37, vcc, 1.0, v1, 1.0
	v_mul_f32_e32 v58, v37, v36
	v_fma_f32 v59, -v35, v58, v37
	v_fmac_f32_e32 v58, v59, v36
	v_fma_f32 v35, -v35, v58, v37
	v_div_fmas_f32 v35, v35, v36, v58
	v_div_fixup_f32 v36, v35, v1, 1.0
	v_pk_mul_f32 v[58:59], v[76:77], v[36:37] op_sel_hi:[1,0]
	s_nop 0
	v_pk_mul_f32 v[58:59], v[40:41], v[58:59]
	s_nop 0
	v_pk_mul_f32 v[58:59], v[58:59], v[60:61]
	v_lshlrev_b32_e32 v60, 16, v114
	v_cvt_pk_bf16_f32 v37, v58, v59
	v_pk_mul_f32 v[58:59], v[74:75], v[36:37] op_sel_hi:[1,0]
	v_and_b32_e32 v61, 0xffff0000, v114
	v_pk_mul_f32 v[58:59], v[38:39], v[58:59]
	s_nop 0
	v_pk_mul_f32 v[58:59], v[58:59], v[60:61]
	s_nop 0
	v_cvt_pk_bf16_f32 v36, v58, v59
	v_mad_u64_u32 v[58:59], s[0:1], v112, s0, v[100:101]
	v_mad_i32_i24 v59, s19, v230, v59
	global_store_dwordx2 v[58:59], v[36:37], off
	s_or_b64 exec, exec, s[20:21]
	s_and_saveexec_b64 s[18:19], s[64:65]
	s_cbranch_execz .LBB0_877
.LBB0_879:
	v_add_u32_e32 v1, 0, v145
	v_add_u32_e32 v1, 0x14400, v1
	ds_read_b128 v[58:61], v1
	ds_read_b128 v[62:65], v1 offset:16
	s_mov_b32 s0, 0xf800000
	s_movk_i32 s5, 0x3000
	s_waitcnt lgkmcnt(0)
	v_mov_b32_e32 v36, v58
	v_mov_b32_e32 v37, v62
	v_mov_b32_e32 v62, v59
	v_mov_b32_e32 v58, v60
	v_mov_b32_e32 v59, v64
	v_mov_b32_e32 v64, v61
	v_pk_add_f32 v[36:37], v[36:37], v[62:63]
	v_pk_add_f32 v[58:59], v[58:59], v[64:65]
	v_lshlrev_b32_e32 v60, 16, v111
	v_pk_add_f32 v[36:37], v[36:37], v[58:59]
	v_and_b32_e32 v61, 0xffff0000, v111
	v_add_f32_e32 v1, v36, v37
	v_fmamk_f32 v1, v1, 0x3c000000, v222
	v_cmp_gt_f32_e32 vcc, s0, v1
	v_mul_f32_e32 v35, 0x4f800000, v1
	s_nop 0
	v_cndmask_b32_e32 v1, v1, v35, vcc
	v_sqrt_f32_e32 v35, v1
	s_nop 0
	v_add_u32_e32 v36, -1, v35
	v_fma_f32 v37, -v36, v35, v1
	v_cmp_ge_f32_e64 s[0:1], 0, v37
	v_add_u32_e32 v37, 1, v35
	s_nop 0
	v_cndmask_b32_e64 v36, v35, v36, s[0:1]
	v_fma_f32 v35, -v37, v35, v1
	v_cmp_lt_f32_e64 s[0:1], 0, v35
	s_nop 1
	v_cndmask_b32_e64 v35, v36, v37, s[0:1]
	v_mul_f32_e32 v36, 0x37800000, v35
	v_cndmask_b32_e32 v35, v35, v36, vcc
	v_cmp_class_f32_e32 vcc, v1, v223
	s_nop 1
	v_cndmask_b32_e32 v1, v35, v1, vcc
	v_div_scale_f32 v35, s[0:1], v1, v1, 1.0
	v_rcp_f32_e32 v36, v35
	s_nop 0
	v_fma_f32 v37, -v35, v36, 1.0
	v_fmac_f32_e32 v36, v37, v36
	v_div_scale_f32 v37, vcc, 1.0, v1, 1.0
	v_mul_f32_e32 v58, v37, v36
	v_fma_f32 v59, -v35, v58, v37
	v_fmac_f32_e32 v58, v59, v36
	v_fma_f32 v35, -v35, v58, v37
	v_div_fmas_f32 v35, v35, v36, v58
	v_div_fixup_f32 v36, v35, v1, 1.0
	v_pk_mul_f32 v[58:59], v[72:73], v[36:37] op_sel_hi:[1,0]
	s_nop 0
	v_pk_mul_f32 v[58:59], v[40:41], v[58:59]
	s_nop 0
	v_pk_mul_f32 v[58:59], v[58:59], v[60:61]
	v_lshlrev_b32_e32 v60, 16, v110
	v_cvt_pk_bf16_f32 v37, v58, v59
	v_pk_mul_f32 v[58:59], v[70:71], v[36:37] op_sel_hi:[1,0]
	v_and_b32_e32 v61, 0xffff0000, v110
	v_pk_mul_f32 v[58:59], v[38:39], v[58:59]
	s_nop 0
	v_pk_mul_f32 v[58:59], v[58:59], v[60:61]
	s_nop 0
	v_cvt_pk_bf16_f32 v36, v58, v59
	v_mad_u64_u32 v[58:59], s[0:1], v108, s5, v[100:101]
	v_mad_i32_i24 v59, v109, s5, v59
	global_store_dwordx2 v[58:59], v[36:37], off
	s_or_b64 exec, exec, s[18:19]
	s_and_saveexec_b64 s[18:19], s[62:63]
	s_cbranch_execz .LBB0_822
.LBB0_880:
	v_add_u32_e32 v1, 0, v146
	v_add_u32_e32 v1, 0x14400, v1
	ds_read_b128 v[58:61], v1
	ds_read_b128 v[62:65], v1 offset:16
	s_mov_b32 s0, 0xf800000
	s_movk_i32 s5, 0x3000
	s_waitcnt lgkmcnt(0)
	v_mov_b32_e32 v36, v58
	v_mov_b32_e32 v37, v62
	v_mov_b32_e32 v62, v59
	v_mov_b32_e32 v58, v60
	v_mov_b32_e32 v59, v64
	v_mov_b32_e32 v64, v61
	v_pk_add_f32 v[36:37], v[36:37], v[62:63]
	v_pk_add_f32 v[58:59], v[58:59], v[64:65]
	v_lshlrev_b32_e32 v60, 16, v107
	v_pk_add_f32 v[36:37], v[36:37], v[58:59]
	v_and_b32_e32 v61, 0xffff0000, v107
	v_add_f32_e32 v1, v36, v37
	v_fmamk_f32 v1, v1, 0x3c000000, v222
	v_cmp_gt_f32_e32 vcc, s0, v1
	v_mul_f32_e32 v35, 0x4f800000, v1
	s_nop 0
	v_cndmask_b32_e32 v1, v1, v35, vcc
	v_sqrt_f32_e32 v35, v1
	s_nop 0
	v_add_u32_e32 v36, -1, v35
	v_fma_f32 v37, -v36, v35, v1
	v_cmp_ge_f32_e64 s[0:1], 0, v37
	v_add_u32_e32 v37, 1, v35
	s_nop 0
	v_cndmask_b32_e64 v36, v35, v36, s[0:1]
	v_fma_f32 v35, -v37, v35, v1
	v_cmp_lt_f32_e64 s[0:1], 0, v35
	s_nop 1
	v_cndmask_b32_e64 v35, v36, v37, s[0:1]
	v_mul_f32_e32 v36, 0x37800000, v35
	v_cndmask_b32_e32 v35, v35, v36, vcc
	v_cmp_class_f32_e32 vcc, v1, v223
	s_nop 1
	v_cndmask_b32_e32 v1, v35, v1, vcc
	v_div_scale_f32 v35, s[0:1], v1, v1, 1.0
	v_rcp_f32_e32 v36, v35
	s_nop 0
	v_fma_f32 v37, -v35, v36, 1.0
	v_fmac_f32_e32 v36, v37, v36
	v_div_scale_f32 v37, vcc, 1.0, v1, 1.0
	v_mul_f32_e32 v58, v37, v36
	v_fma_f32 v59, -v35, v58, v37
	v_fmac_f32_e32 v58, v59, v36
	v_fma_f32 v35, -v35, v58, v37
	v_div_fmas_f32 v35, v35, v36, v58
	v_div_fixup_f32 v36, v35, v1, 1.0
	v_pk_mul_f32 v[58:59], v[68:69], v[36:37] op_sel_hi:[1,0]
	s_nop 0
	v_pk_mul_f32 v[58:59], v[40:41], v[58:59]
	s_nop 0
	v_pk_mul_f32 v[58:59], v[58:59], v[60:61]
	v_lshlrev_b32_e32 v60, 16, v106
	v_cvt_pk_bf16_f32 v37, v58, v59
	v_pk_mul_f32 v[58:59], v[66:67], v[36:37] op_sel_hi:[1,0]
	v_and_b32_e32 v61, 0xffff0000, v106
	v_pk_mul_f32 v[58:59], v[38:39], v[58:59]
	s_nop 0
	v_pk_mul_f32 v[58:59], v[58:59], v[60:61]
	s_nop 0
	v_cvt_pk_bf16_f32 v36, v58, v59
	v_mad_u64_u32 v[58:59], s[0:1], v104, s5, v[100:101]
	v_mad_i32_i24 v59, v105, s5, v59
	global_store_dwordx2 v[58:59], v[36:37], off
	s_branch .LBB0_822
